# SO8 (L2 prefetch of block tb+2 raw rows by waves 4-7) on SO7, second measurement
# speedup vs baseline: 1.0169x; 1.0000x over previous
.LBB0_382:
	s_andn2_b64 vcc, exec, s[10:11]
	s_cbranch_vccnz .LBB0_454
	s_and_b64 s[10:11], s[12:13], exec
	s_cselect_b32 s10, 4, 2
	s_lshr_b32 s5, s0, 7
	s_lshl_b32 s7, s5, 12
	s_lshl_b32 s3, s1, 3
	s_add_i32 s33, s74, -1
	s_add_i32 s75, s7, 0
	s_bfe_u32 s11, s0, 0x10006
	s_bitcmp1_b32 s0, 6
	s_cselect_b64 s[88:89], -1, 0
	s_and_b32 s0, s0, 0x3fffff80
	s_lshl_b32 s0, s0, 2
	s_add_i32 s62, s0, 0
	s_lshl_b32 s0, s1, 12
	s_add_i32 s7, s0, 0
	s_lshl_b32 s0, s1, 10
	s_lshl_b32 s77, s5, 10
	s_add_i32 s0, s0, 0
	s_lshl_b32 s5, s1, 11
	s_add_i32 s44, s0, 0x1e800
	s_add_i32 s51, s0, 0x1a800
	s_add_i32 s5, s5, 0
	s_add_i32 s18, s0, 0x1b800
	s_add_i32 s12, s1, -4
	s_lshl_b32 s0, s30, 16
	s_lshl_b32 s13, s56, 12
	s_add_i32 s76, s75, 0x14800
	s_add_i32 s62, s62, 0x1f800
	s_add_i32 s63, s74, 0xffffff80
	s_lshl_b32 s59, s56, 6
	s_add_i32 s5, s5, 0x1c800
	s_or_b32 s14, s13, s0
	s_lshl_b32 s13, s12, 1
	s_add_i32 s71, s74, -8
	s_lshl_b32 s0, s12, 4
	s_cmp_lt_u32 s1, s10
	s_cselect_b64 s[90:91], -1, 0
	s_lshl_b32 s12, s12, 11
	v_readlane_b32 s16, v255, 29
	s_add_i32 s34, s12, 0
	s_or_b32 s12, s13, 1
	v_readlane_b32 s17, v255, 30
	s_lshl_b32 s60, s12, 3
	s_lshl_b32 s12, s12, 10
	s_lshl_b32 s10, s11, 10
	s_lshl_b32 s35, s1, 5
	s_lshl_b32 s15, s30, 11
	s_lshl_b32 s11, s11, 5
	s_nor_b64 s[92:93], s[82:83], s[16:17]
	s_add_i32 s61, s12, 0
	s_lshl_b32 s12, s56, 3
	v_readlane_b32 s13, v255, 23
	s_add_u32 s12, s13, s12
	v_readlane_b32 s13, v255, 24
	s_addc_u32 s13, s13, 0
	s_lshl_b32 s16, s30, 2
	s_add_u32 s94, s12, s16
	s_addc_u32 s95, s13, 0
	s_lshl_b32 s12, s30, 7
	s_add_u32 s96, s54, s12
	s_addc_u32 s97, s55, 0
	s_lshl_b32 s12, s56, 7
	s_add_u32 s54, s36, s12
	s_addc_u32 s55, s37, 0
	s_add_u32 s52, s52, s12
	s_addc_u32 s53, s53, 0
	s_add_u32 s12, s42, s12
	s_addc_u32 s13, s43, 0
	s_add_i32 s15, s81, s15
	s_add_i32 s15, s15, s31
	v_writelane_b32 v255, s56, 59
	s_mov_b32 s42, s18
	s_add_i32 s66, s48, s33
	s_add_i32 s67, s15, 0x800
	s_or_b32 s70, s10, 0x18800
	s_lshl_b32 s30, s14, 1
	s_lshl_b32 s72, s11, 1
	v_lshrrev_b32_e32 v34, 3, v1
	v_and_b32_e32 v35, 7, v1
	v_lshlrev_b32_e32 v35, 4, v35
	v_add_u32_e32 v34, s3, v34
	v_mov_b32_e32 v36, s12
	v_mov_b32_e32 v37, s13
	v_mov_b32_e32 v38, s52
	v_mov_b32_e32 v39, s53
	v_mov_b32_e32 v40, s54
	v_mov_b32_e32 v41, s55
	v_mov_b32_e32 v42, s96
	v_mov_b32_e32 v43, s97
	v_lshl_add_u64 v[44:45], v[42:43], 0, s[68:69]
	v_mov_b32_e32 v49, 0x800
	v_mov_b32_e32 v50, 0x200
	v_mov_b32_e32 v46, v34
	v_min_i32_e32 v46, 0x149, v46
	v_mul_hi_i32 v47, v46, s6
	v_ashrrev_i32_e32 v47, 1, v47
	v_mul_u32_u24_e32 v48, 5, v47
	v_sub_u32_e32 v48, v46, v48
	v_mov_b32_e32 v226, v47
	v_cmp_gt_u32_e32 vcc, 3, v48
	v_mov_b32_e32 v51, v36
	v_mov_b32_e32 v52, v37
	v_cndmask_b32_e32 v227, v50, v49, vcc
	v_cmp_eq_u32_e32 vcc, 1, v48
	s_nop 1
	v_cndmask_b32_e32 v51, v51, v38, vcc
	v_cndmask_b32_e32 v52, v52, v39, vcc
	v_cmp_eq_u32_e32 vcc, 2, v48
	s_nop 1
	v_cndmask_b32_e32 v51, v51, v40, vcc
	v_cndmask_b32_e32 v52, v52, v41, vcc
	v_cmp_eq_u32_e32 vcc, 3, v48
	s_nop 1
	v_cndmask_b32_e32 v51, v51, v42, vcc
	v_cndmask_b32_e32 v52, v52, v43, vcc
	v_cmp_eq_u32_e32 vcc, 4, v48
	s_nop 1
	v_cndmask_b32_e32 v51, v51, v44, vcc
	v_cndmask_b32_e32 v52, v52, v45, vcc
	v_mul_lo_u32 v53, s48, v227
	v_add_u32_e32 v53, v53, v35
	v_add_co_u32_e32 v228, vcc, v51, v53
	s_nop 1
	v_addc_co_u32_e32 v229, vcc, 0, v52, vcc
	v_add_u32_e32 v46, 64, v34
	v_min_i32_e32 v46, 0x149, v46
	v_mul_hi_i32 v47, v46, s6
	v_ashrrev_i32_e32 v47, 1, v47
	v_mul_u32_u24_e32 v48, 5, v47
	v_sub_u32_e32 v48, v46, v48
	v_mov_b32_e32 v230, v47
	v_cmp_gt_u32_e32 vcc, 3, v48
	v_mov_b32_e32 v51, v36
	v_mov_b32_e32 v52, v37
	v_cndmask_b32_e32 v231, v50, v49, vcc
	v_cmp_eq_u32_e32 vcc, 1, v48
	s_nop 1
	v_cndmask_b32_e32 v51, v51, v38, vcc
	v_cndmask_b32_e32 v52, v52, v39, vcc
	v_cmp_eq_u32_e32 vcc, 2, v48
	s_nop 1
	v_cndmask_b32_e32 v51, v51, v40, vcc
	v_cndmask_b32_e32 v52, v52, v41, vcc
	v_cmp_eq_u32_e32 vcc, 3, v48
	s_nop 1
	v_cndmask_b32_e32 v51, v51, v42, vcc
	v_cndmask_b32_e32 v52, v52, v43, vcc
	v_cmp_eq_u32_e32 vcc, 4, v48
	s_nop 1
	v_cndmask_b32_e32 v51, v51, v44, vcc
	v_cndmask_b32_e32 v52, v52, v45, vcc
	v_mul_lo_u32 v53, s48, v231
	v_add_u32_e32 v53, v53, v35
	v_add_co_u32_e32 v232, vcc, v51, v53
	s_nop 1
	v_addc_co_u32_e32 v233, vcc, 0, v52, vcc
	v_add_u32_e32 v46, 128, v34
	v_min_i32_e32 v46, 0x149, v46
	v_mul_hi_i32 v47, v46, s6
	v_ashrrev_i32_e32 v47, 1, v47
	v_mul_u32_u24_e32 v48, 5, v47
	v_sub_u32_e32 v48, v46, v48
	v_mov_b32_e32 v234, v47
	v_cmp_gt_u32_e32 vcc, 3, v48
	v_mov_b32_e32 v51, v36
	v_mov_b32_e32 v52, v37
	v_cndmask_b32_e32 v235, v50, v49, vcc
	v_cmp_eq_u32_e32 vcc, 1, v48
	s_nop 1
	v_cndmask_b32_e32 v51, v51, v38, vcc
	v_cndmask_b32_e32 v52, v52, v39, vcc
	v_cmp_eq_u32_e32 vcc, 2, v48
	s_nop 1
	v_cndmask_b32_e32 v51, v51, v40, vcc
	v_cndmask_b32_e32 v52, v52, v41, vcc
	v_cmp_eq_u32_e32 vcc, 3, v48
	s_nop 1
	v_cndmask_b32_e32 v51, v51, v42, vcc
	v_cndmask_b32_e32 v52, v52, v43, vcc
	v_cmp_eq_u32_e32 vcc, 4, v48
	s_nop 1
	v_cndmask_b32_e32 v51, v51, v44, vcc
	v_cndmask_b32_e32 v52, v52, v45, vcc
	v_mul_lo_u32 v53, s48, v235
	v_add_u32_e32 v53, v53, v35
	v_add_co_u32_e32 v236, vcc, v51, v53
	s_nop 1
	v_addc_co_u32_e32 v237, vcc, 0, v52, vcc
	v_add_u32_e32 v46, 192, v34
	v_min_i32_e32 v46, 0x149, v46
	v_mul_hi_i32 v47, v46, s6
	v_ashrrev_i32_e32 v47, 1, v47
	v_mul_u32_u24_e32 v48, 5, v47
	v_sub_u32_e32 v48, v46, v48
	v_mov_b32_e32 v238, v47
	v_cmp_gt_u32_e32 vcc, 3, v48
	v_mov_b32_e32 v51, v36
	v_mov_b32_e32 v52, v37
	v_cndmask_b32_e32 v239, v50, v49, vcc
	v_cmp_eq_u32_e32 vcc, 1, v48
	s_nop 1
	v_cndmask_b32_e32 v51, v51, v38, vcc
	v_cndmask_b32_e32 v52, v52, v39, vcc
	v_cmp_eq_u32_e32 vcc, 2, v48
	s_nop 1
	v_cndmask_b32_e32 v51, v51, v40, vcc
	v_cndmask_b32_e32 v52, v52, v41, vcc
	v_cmp_eq_u32_e32 vcc, 3, v48
	s_nop 1
	v_cndmask_b32_e32 v51, v51, v42, vcc
	v_cndmask_b32_e32 v52, v52, v43, vcc
	v_cmp_eq_u32_e32 vcc, 4, v48
	s_nop 1
	v_cndmask_b32_e32 v51, v51, v44, vcc
	v_cndmask_b32_e32 v52, v52, v45, vcc
	v_mul_lo_u32 v53, s48, v239
	v_add_u32_e32 v53, v53, v35
	v_add_co_u32_e32 v240, vcc, v51, v53
	s_nop 1
	v_addc_co_u32_e32 v241, vcc, 0, v52, vcc
	v_add_u32_e32 v46, 256, v34
	v_min_i32_e32 v46, 0x149, v46
	v_mul_hi_i32 v47, v46, s6
	v_ashrrev_i32_e32 v47, 1, v47
	v_mul_u32_u24_e32 v48, 5, v47
	v_sub_u32_e32 v48, v46, v48
	v_mov_b32_e32 v242, v47
	v_cmp_gt_u32_e32 vcc, 3, v48
	v_mov_b32_e32 v51, v36
	v_mov_b32_e32 v52, v37
	v_cndmask_b32_e32 v243, v50, v49, vcc
	v_cmp_eq_u32_e32 vcc, 1, v48
	s_nop 1
	v_cndmask_b32_e32 v51, v51, v38, vcc
	v_cndmask_b32_e32 v52, v52, v39, vcc
	v_cmp_eq_u32_e32 vcc, 2, v48
	s_nop 1
	v_cndmask_b32_e32 v51, v51, v40, vcc
	v_cndmask_b32_e32 v52, v52, v41, vcc
	v_cmp_eq_u32_e32 vcc, 3, v48
	s_nop 1
	v_cndmask_b32_e32 v51, v51, v42, vcc
	v_cndmask_b32_e32 v52, v52, v43, vcc
	v_cmp_eq_u32_e32 vcc, 4, v48
	s_nop 1
	v_cndmask_b32_e32 v51, v51, v44, vcc
	v_cndmask_b32_e32 v52, v52, v45, vcc
	v_mul_lo_u32 v53, s48, v243
	v_add_u32_e32 v53, v53, v35
	v_add_co_u32_e32 v244, vcc, v51, v53
	s_nop 1
	v_addc_co_u32_e32 v245, vcc, 0, v52, vcc
	v_add_u32_e32 v46, 320, v34
	v_min_i32_e32 v46, 0x149, v46
	v_mul_hi_i32 v47, v46, s6
	v_ashrrev_i32_e32 v47, 1, v47
	v_mul_u32_u24_e32 v48, 5, v47
	v_sub_u32_e32 v48, v46, v48
	v_mov_b32_e32 v246, v47
	v_cmp_gt_u32_e32 vcc, 3, v48
	v_mov_b32_e32 v51, v36
	v_mov_b32_e32 v52, v37
	v_cndmask_b32_e32 v247, v50, v49, vcc
	v_cmp_eq_u32_e32 vcc, 1, v48
	s_nop 1
	v_cndmask_b32_e32 v51, v51, v38, vcc
	v_cndmask_b32_e32 v52, v52, v39, vcc
	v_cmp_eq_u32_e32 vcc, 2, v48
	s_nop 1
	v_cndmask_b32_e32 v51, v51, v40, vcc
	v_cndmask_b32_e32 v52, v52, v41, vcc
	v_cmp_eq_u32_e32 vcc, 3, v48
	s_nop 1
	v_cndmask_b32_e32 v51, v51, v42, vcc
	v_cndmask_b32_e32 v52, v52, v43, vcc
	v_cmp_eq_u32_e32 vcc, 4, v48
	s_nop 1
	v_cndmask_b32_e32 v51, v51, v44, vcc
	v_cndmask_b32_e32 v52, v52, v45, vcc
	v_mul_lo_u32 v53, s48, v247
	v_add_u32_e32 v53, v53, v35
	v_add_co_u32_e32 v248, vcc, v51, v53
	s_nop 1
	v_addc_co_u32_e32 v249, vcc, 0, v52, vcc
	s_add_u32 s10, s96, s68
	s_addc_u32 s11, s97, s69
	v_writelane_b32 v254, s12, 0
	v_writelane_b32 v254, s13, 1
	v_writelane_b32 v254, s52, 2
	v_writelane_b32 v254, s53, 3
	v_writelane_b32 v254, s54, 4
	v_writelane_b32 v254, s55, 5
	v_writelane_b32 v254, s96, 6
	v_writelane_b32 v254, s97, 7
	v_writelane_b32 v254, s10, 8
	v_writelane_b32 v254, s11, 9
	v_readlane_b32 s10, v255, 25
	v_readlane_b32 s11, v255, 26
	v_lshlrev_b32_e32 v34, 7, v1
	v_lshrrev_b32_e32 v36, 1, v1
	v_and_b32_e32 v34, 0x780, v34
	v_and_b32_e32 v36, -8, v36
	v_mov_b32_e32 v35, 0
	v_lshl_add_u32 v34, v36, 1, v34
	s_lshr_b32 s12, s1, 2
	s_lshl_b32 s12, s12, 18
	s_and_b32 s13, s1, 3
	s_lshl_b32 s13, s13, 11
	s_add_i32 s12, s12, s13
	s_add_i32 s12, s12, s30
	s_mov_b32 s13, 0
	v_lshl_add_u64 v[36:37], s[10:11], 0, v[34:35]
	v_lshl_add_u64 v[36:37], v[36:37], 0, s[12:13]
	s_lshl_b32 s12, s1, 11
	s_add_i32 s12, s12, 0x24000
	s_mov_b32 s13, m0
	s_mov_b32 m0, s12
	s_nop 0
	global_load_lds_dwordx4 v[36:37], off
	s_add_i32 s12, s12, 0x3c0
	s_mov_b32 m0, s12
	s_nop 0
	global_load_lds_dwordx4 v[36:37], off offset:64
	s_mov_b32 m0, s13
	s_branch .LBB0_385

.LBB0_436:
	s_waitcnt vmcnt(0)
	s_branch .Lso8_join
.Lso8_pf:
	s_and_b64 s[10:11], s[8:9], exec
	s_movk_i32 s14, 0xffc1
	s_cselect_b32 s14, 0x41, s14
	s_add_i32 s14, s22, s14
	v_add_u32_e32 v250, s14, v1
	v_med3_i32 v250, v250, 0, s33
	v_add_u32_e32 v250, s48, v250
	s_sub_i32 s15, s1, 4
	s_lshl_b32 s15, s15, 1
	s_cmp_eq_u32 s1, 7
	s_cselect_b32 s16, 9, 11
	v_lshlrev_b32_e32 v251, s16, v250
	v_readlane_b32 s10, v254, s15
	s_add_i32 s15, s15, 1
	v_readlane_b32 s11, v254, s15
	s_nop 4
	global_load_dword v214, v251, s[10:11]
	s_cmp_lg_u32 s1, 7
	s_cbranch_scc1 .Lso8_one
	v_readlane_b32 s10, v254, 8
	v_readlane_b32 s11, v254, 9
	s_nop 4
	global_load_dword v225, v251, s[10:11]
	s_waitcnt vmcnt(2)
	s_branch .Lso8_join
.Lso8_one:
	s_waitcnt vmcnt(1)
.Lso8_join:
	s_or_b64 s[10:11], s[82:83], s[56:57]
	s_and_b64 vcc, exec, s[10:11]
	s_waitcnt lgkmcnt(0)
	s_barrier
	s_cbranch_vccnz .LBB0_438
	s_lshl_b32 s15, s49, 6
	s_sub_i32 s16, s63, s73
	s_add_i32 s17, s15, s0
	s_sub_i32 s18, s71, s17
	s_add_i32 s14, s15, s60
	s_sub_i32 s31, s71, s14
	s_and_b64 s[10:11], s[8:9], exec
	s_cselect_b32 s16, s15, s16
	s_cselect_b32 s17, s17, s18
	s_cselect_b32 s14, s14, s31
	v_lshrrev_b32_e32 v136, 3, v1
	v_and_b32_e32 v137, 7, v1
	v_lshlrev_b32_e32 v143, 4, v1
	v_mov_b32_e32 v144, 0
	v_mov_b32_e32 v145, 0
	v_mov_b32_e32 v146, 0
	v_mov_b32_e32 v147, 0
	v_add_u32_e32 v143, 0x22f00, v143
	v_lshlrev_b32_e32 v138, 4, v137
	v_add_u32_e32 v139, s17, v136
	v_add_u32_e32 v140, s14, v136
	ds_write_b128 v143, v[144:147]
	v_subrev_u32_e32 v98, s16, v139
	v_subrev_u32_e32 v99, s16, v140
	v_cmp_lt_i32_e32 vcc, 0, v139
	v_mad_u32_u24 v98, v98, s58, v138
	v_mad_u32_u24 v99, v99, s58, v138
	v_mov_b32_e32 v141, 0x1a580
	v_mov_b32_e32 v142, 0x1a080
	v_cndmask_b32_e32 v100, v141, v98, vcc
	v_cmp_gt_i32_e32 vcc, s33, v139
	v_lshlrev_b32_e32 v148, 5, v137
	v_add_u32_e32 v148, 0x22000, v148
	v_cndmask_b32_e32 v101, v142, v98, vcc
	v_cmp_lt_i32_e32 vcc, 0, v140
	ds_read_b128 v[168:171], v100 offset:35200
	ds_read_b128 v[172:175], v98 offset:35840
	ds_read_b128 v[176:179], v101 offset:36480
	ds_read_b128 v[192:195], v148 offset:768
	ds_read_b128 v[196:199], v148 offset:784
	v_cndmask_b32_e32 v220, v141, v99, vcc
	v_cmp_gt_i32_e32 vcc, s33, v140
	ds_read_b128 v[200:203], v148 offset:1024
	ds_read_b128 v[204:207], v148 offset:1040
	v_sub_u32_e32 v149, 7, v136
	v_cndmask_b32_e32 v221, v142, v99, vcc
	ds_read_b128 v[180:183], v100 offset:35328
	ds_read_b128 v[184:187], v98 offset:35968
	ds_read_b128 v[188:191], v101 offset:36608
	v_cndmask_b32_e64 v149, v149, v136, s[8:9]
	v_lshl_add_u32 v149, v149, 7, v138
	v_add_u32_e32 v222, s34, v149
	v_add_u32_e32 v223, s61, v149
	v_lshlrev_b32_e32 v224, 4, v1
	v_add_u32_e32 v224, 0x24000, v224
	s_waitcnt lgkmcnt(7)
	v_lshlrev_b32_e32 v136, 16, v168
	v_lshlrev_b32_e32 v138, 16, v176
	v_and_b32_e32 v137, 0xffff0000, v168
	v_lshlrev_b32_e32 v140, 16, v172
	v_and_b32_e32 v139, 0xffff0000, v176
	v_lshlrev_b32_e32 v142, 16, v169
	v_add_f32_e32 v136, v138, v136
	v_and_b32_e32 v141, 0xffff0000, v172
	v_lshlrev_b32_e32 v144, 16, v177
	v_and_b32_e32 v143, 0xffff0000, v169
	v_fma_f32 v136, v136, 0.5, -v140
	v_add_f32_e32 v137, v139, v137
	v_lshlrev_b32_e32 v146, 16, v173
	v_and_b32_e32 v145, 0xffff0000, v177
	v_lshlrev_b32_e32 v148, 16, v170
	s_waitcnt lgkmcnt(5)
	v_fmac_f32_e32 v140, v192, v136
	v_fma_f32 v137, v137, 0.5, -v141
	v_add_f32_e32 v142, v144, v142
	v_and_b32_e32 v147, 0xffff0000, v173
	v_lshlrev_b32_e32 v150, 16, v178
	v_and_b32_e32 v149, 0xffff0000, v170
	v_mul_f32_e32 v140, 0x4038aa3b, v140
	v_fmac_f32_e32 v141, v193, v137
	v_fma_f32 v142, v142, 0.5, -v146
	v_add_f32_e32 v143, v145, v143
	v_lshlrev_b32_e32 v152, 16, v174
	v_and_b32_e32 v151, 0xffff0000, v178
	v_lshlrev_b32_e32 v154, 16, v171
	v_exp_f32_e32 v140, v140
	v_mul_f32_e32 v141, 0x4038aa3b, v141
	v_fmac_f32_e32 v146, v194, v142
	v_fma_f32 v143, v143, 0.5, -v147
	v_add_f32_e32 v148, v150, v148
	v_and_b32_e32 v153, 0xffff0000, v174
	v_lshlrev_b32_e32 v156, 16, v179
	v_and_b32_e32 v155, 0xffff0000, v171
	v_add_f32_e32 v140, 1.0, v140
	v_exp_f32_e32 v141, v141
	v_mul_f32_e32 v146, 0x4038aa3b, v146
	v_fmac_f32_e32 v147, v195, v143
	v_fma_f32 v148, v148, 0.5, -v152
	v_add_f32_e32 v149, v151, v149
	v_lshlrev_b32_e32 v158, 16, v175
	v_and_b32_e32 v157, 0xffff0000, v179
	v_rcp_f32_e32 v140, v140
	v_add_f32_e32 v141, 1.0, v141
	v_exp_f32_e32 v146, v146
	v_mul_f32_e32 v147, 0x4038aa3b, v147
	v_fmac_f32_e32 v152, v196, v148
	v_fma_f32 v149, v149, 0.5, -v153
	v_add_f32_e32 v154, v156, v154
	v_and_b32_e32 v159, 0xffff0000, v175
	ds_read_b128 v[168:171], v220 offset:35200
	ds_read_b128 v[172:175], v99 offset:35840
	ds_read_b128 v[176:179], v221 offset:36480
	v_fma_f32 v140, -v140, 2.0, 1.0
	v_rcp_f32_e32 v141, v141
	v_add_f32_e32 v146, 1.0, v146
	v_exp_f32_e32 v147, v147
	v_mul_f32_e32 v152, 0x4038aa3b, v152
	v_fmac_f32_e32 v153, v197, v149
	v_fma_f32 v154, v154, 0.5, -v158
	v_add_f32_e32 v155, v157, v155
	v_fma_f32 v141, -v141, 2.0, 1.0
	v_rcp_f32_e32 v146, v146
	v_add_f32_e32 v147, 1.0, v147
	v_exp_f32_e32 v152, v152
	v_mul_f32_e32 v153, 0x4038aa3b, v153
	v_fmac_f32_e32 v158, v198, v154
	v_fma_f32 v155, v155, 0.5, -v159
	s_waitcnt lgkmcnt(3)
	v_lshlrev_b32_e32 v136, 16, v180
	v_cvt_pk_bf16_f32 v160, v140, v141
	v_fma_f32 v146, -v146, 2.0, 1.0
	v_rcp_f32_e32 v147, v147
	v_add_f32_e32 v152, 1.0, v152
	v_exp_f32_e32 v153, v153
	v_mul_f32_e32 v158, 0x4038aa3b, v158
	v_fmac_f32_e32 v159, v199, v155
	v_lshlrev_b32_e32 v138, 16, v188
	v_and_b32_e32 v137, 0xffff0000, v180
	v_fma_f32 v147, -v147, 2.0, 1.0
	v_rcp_f32_e32 v152, v152
	v_add_f32_e32 v153, 1.0, v153
	v_exp_f32_e32 v158, v158
	v_mul_f32_e32 v159, 0x4038aa3b, v159
	v_lshlrev_b32_e32 v140, 16, v184
	v_and_b32_e32 v139, 0xffff0000, v188
	v_lshlrev_b32_e32 v142, 16, v181
	v_cvt_pk_bf16_f32 v161, v146, v147
	v_fma_f32 v152, -v152, 2.0, 1.0
	v_rcp_f32_e32 v153, v153
	v_add_f32_e32 v158, 1.0, v158
	v_exp_f32_e32 v159, v159
	v_add_f32_e32 v136, v138, v136
	v_and_b32_e32 v141, 0xffff0000, v184
	v_lshlrev_b32_e32 v144, 16, v189
	v_and_b32_e32 v143, 0xffff0000, v181
	v_fma_f32 v153, -v153, 2.0, 1.0
	v_rcp_f32_e32 v158, v158
	v_add_f32_e32 v159, 1.0, v159
	v_fma_f32 v136, v136, 0.5, -v140
	v_add_f32_e32 v137, v139, v137
	v_lshlrev_b32_e32 v146, 16, v185
	v_and_b32_e32 v145, 0xffff0000, v189
	v_lshlrev_b32_e32 v148, 16, v182
	v_cvt_pk_bf16_f32 v162, v152, v153
	v_fma_f32 v158, -v158, 2.0, 1.0
	v_rcp_f32_e32 v159, v159
	v_fmac_f32_e32 v140, v200, v136
	v_fma_f32 v137, v137, 0.5, -v141
	v_add_f32_e32 v142, v144, v142
	v_and_b32_e32 v147, 0xffff0000, v185
	v_lshlrev_b32_e32 v150, 16, v190
	v_and_b32_e32 v149, 0xffff0000, v182
	v_fma_f32 v159, -v159, 2.0, 1.0
	v_fmac_f32_e32 v141, v201, v137
	v_fma_f32 v142, v142, 0.5, -v146
	v_add_f32_e32 v143, v145, v143
	v_lshlrev_b32_e32 v152, 16, v186
	v_and_b32_e32 v151, 0xffff0000, v190
	v_lshlrev_b32_e32 v154, 16, v183
	v_cvt_pk_bf16_f32 v163, v158, v159
	ds_write_b128 v222, v[160:163] offset:16384
	s_waitcnt lgkmcnt(1)
	v_lshlrev_b32_e32 v136, 16, v168
	v_cvt_pk_bf16_f32 v216, v140, v141
	v_fmac_f32_e32 v146, v202, v142
	v_fma_f32 v143, v143, 0.5, -v147
	v_add_f32_e32 v148, v150, v148
	v_and_b32_e32 v153, 0xffff0000, v186
	v_lshlrev_b32_e32 v156, 16, v191
	v_and_b32_e32 v155, 0xffff0000, v183
	v_lshlrev_b32_e32 v138, 16, v176
	v_and_b32_e32 v137, 0xffff0000, v168
	v_fmac_f32_e32 v147, v203, v143
	v_fma_f32 v148, v148, 0.5, -v152
	v_add_f32_e32 v149, v151, v149
	v_lshlrev_b32_e32 v158, 16, v187
	v_and_b32_e32 v157, 0xffff0000, v191
	v_lshlrev_b32_e32 v140, 16, v172
	v_and_b32_e32 v139, 0xffff0000, v176
	v_lshlrev_b32_e32 v142, 16, v169
	v_cvt_pk_bf16_f32 v217, v146, v147
	v_fmac_f32_e32 v152, v204, v148
	v_fma_f32 v149, v149, 0.5, -v153
	v_add_f32_e32 v154, v156, v154
	v_and_b32_e32 v159, 0xffff0000, v187
	ds_read_b128 v[180:183], v220 offset:35328
	ds_read_b128 v[184:187], v99 offset:35968
	ds_read_b128 v[188:191], v221 offset:36608
	v_add_f32_e32 v136, v138, v136
	v_and_b32_e32 v141, 0xffff0000, v172
	v_lshlrev_b32_e32 v144, 16, v177
	v_and_b32_e32 v143, 0xffff0000, v169
	v_fmac_f32_e32 v153, v205, v149
	v_fma_f32 v154, v154, 0.5, -v158
	v_add_f32_e32 v155, v157, v155
	v_fma_f32 v136, v136, 0.5, -v140
	v_add_f32_e32 v137, v139, v137
	v_lshlrev_b32_e32 v146, 16, v173
	v_and_b32_e32 v145, 0xffff0000, v177
	v_lshlrev_b32_e32 v148, 16, v170
	v_cvt_pk_bf16_f32 v218, v152, v153
	v_fmac_f32_e32 v158, v206, v154
	v_fma_f32 v155, v155, 0.5, -v159
	v_fmac_f32_e32 v140, v192, v136
	v_fma_f32 v137, v137, 0.5, -v141
	v_add_f32_e32 v142, v144, v142
	v_and_b32_e32 v147, 0xffff0000, v173
	v_lshlrev_b32_e32 v150, 16, v178
	v_and_b32_e32 v149, 0xffff0000, v170
	v_fmac_f32_e32 v159, v207, v155
	v_mul_f32_e32 v140, 0x4038aa3b, v140
	v_fmac_f32_e32 v141, v193, v137
	v_fma_f32 v142, v142, 0.5, -v146
	v_add_f32_e32 v143, v145, v143
	v_lshlrev_b32_e32 v152, 16, v174
	v_and_b32_e32 v151, 0xffff0000, v178
	v_lshlrev_b32_e32 v154, 16, v171
	v_cvt_pk_bf16_f32 v219, v158, v159
	ds_write_b128 v222, v[216:219] offset:24576
	v_exp_f32_e32 v140, v140
	v_mul_f32_e32 v141, 0x4038aa3b, v141
	v_fmac_f32_e32 v146, v194, v142
	v_fma_f32 v143, v143, 0.5, -v147
	v_add_f32_e32 v148, v150, v148
	v_and_b32_e32 v153, 0xffff0000, v174
	v_lshlrev_b32_e32 v156, 16, v179
	v_and_b32_e32 v155, 0xffff0000, v171
	v_add_f32_e32 v140, 1.0, v140
	v_exp_f32_e32 v141, v141
	v_mul_f32_e32 v146, 0x4038aa3b, v146
	v_fmac_f32_e32 v147, v195, v143
	v_fma_f32 v148, v148, 0.5, -v152
	v_add_f32_e32 v149, v151, v149
	v_lshlrev_b32_e32 v158, 16, v175
	v_and_b32_e32 v157, 0xffff0000, v179
	v_rcp_f32_e32 v140, v140
	v_add_f32_e32 v141, 1.0, v141
	v_exp_f32_e32 v146, v146
	v_mul_f32_e32 v147, 0x4038aa3b, v147
	v_fmac_f32_e32 v152, v196, v148
	v_fma_f32 v149, v149, 0.5, -v153
	v_add_f32_e32 v154, v156, v154
	v_and_b32_e32 v159, 0xffff0000, v175
	v_fma_f32 v140, -v140, 2.0, 1.0
	v_rcp_f32_e32 v141, v141
	v_add_f32_e32 v146, 1.0, v146
	v_exp_f32_e32 v147, v147
	v_mul_f32_e32 v152, 0x4038aa3b, v152
	v_fmac_f32_e32 v153, v197, v149
	v_fma_f32 v154, v154, 0.5, -v158
	v_add_f32_e32 v155, v157, v155
	v_fma_f32 v141, -v141, 2.0, 1.0
	v_rcp_f32_e32 v146, v146
	v_add_f32_e32 v147, 1.0, v147
	v_exp_f32_e32 v152, v152
	v_mul_f32_e32 v153, 0x4038aa3b, v153
	v_fmac_f32_e32 v158, v198, v154
	v_fma_f32 v155, v155, 0.5, -v159
	s_waitcnt lgkmcnt(1)
	v_lshlrev_b32_e32 v136, 16, v180
	v_cvt_pk_bf16_f32 v160, v140, v141
	v_fma_f32 v146, -v146, 2.0, 1.0
	v_rcp_f32_e32 v147, v147
	v_add_f32_e32 v152, 1.0, v152
	v_exp_f32_e32 v153, v153
	v_mul_f32_e32 v158, 0x4038aa3b, v158
	v_fmac_f32_e32 v159, v199, v155
	v_lshlrev_b32_e32 v138, 16, v188
	v_and_b32_e32 v137, 0xffff0000, v180
	v_fma_f32 v147, -v147, 2.0, 1.0
	v_rcp_f32_e32 v152, v152
	v_add_f32_e32 v153, 1.0, v153
	v_exp_f32_e32 v158, v158
	v_mul_f32_e32 v159, 0x4038aa3b, v159
	v_lshlrev_b32_e32 v140, 16, v184
	v_and_b32_e32 v139, 0xffff0000, v188
	v_lshlrev_b32_e32 v142, 16, v181
	v_cvt_pk_bf16_f32 v161, v146, v147
	v_fma_f32 v152, -v152, 2.0, 1.0
	v_rcp_f32_e32 v153, v153
	v_add_f32_e32 v158, 1.0, v158
	v_exp_f32_e32 v159, v159
	v_add_f32_e32 v136, v138, v136
	v_and_b32_e32 v141, 0xffff0000, v184
	v_lshlrev_b32_e32 v144, 16, v189
	v_and_b32_e32 v143, 0xffff0000, v181
	v_fma_f32 v153, -v153, 2.0, 1.0
	v_rcp_f32_e32 v158, v158
	v_add_f32_e32 v159, 1.0, v159
	v_fma_f32 v136, v136, 0.5, -v140
	v_add_f32_e32 v137, v139, v137
	v_lshlrev_b32_e32 v146, 16, v185
	v_and_b32_e32 v145, 0xffff0000, v189
	v_lshlrev_b32_e32 v148, 16, v182
	v_cvt_pk_bf16_f32 v162, v152, v153
	v_fma_f32 v158, -v158, 2.0, 1.0
	v_rcp_f32_e32 v159, v159
	v_fmac_f32_e32 v140, v200, v136
	v_fma_f32 v137, v137, 0.5, -v141
	v_add_f32_e32 v142, v144, v142
	v_and_b32_e32 v147, 0xffff0000, v185
	v_lshlrev_b32_e32 v150, 16, v190
	v_and_b32_e32 v149, 0xffff0000, v182
	v_fma_f32 v159, -v159, 2.0, 1.0
	v_fmac_f32_e32 v141, v201, v137
	v_fma_f32 v142, v142, 0.5, -v146
	v_add_f32_e32 v143, v145, v143
	v_lshlrev_b32_e32 v152, 16, v186
	v_and_b32_e32 v151, 0xffff0000, v190
	v_lshlrev_b32_e32 v154, 16, v183
	v_cvt_pk_bf16_f32 v163, v158, v159
	ds_write_b128 v223, v[160:163] offset:16384
	v_cvt_pk_bf16_f32 v216, v140, v141
	v_fmac_f32_e32 v146, v202, v142
	v_fma_f32 v143, v143, 0.5, -v147
	v_add_f32_e32 v148, v150, v148
	v_and_b32_e32 v153, 0xffff0000, v186
	v_lshlrev_b32_e32 v156, 16, v191
	v_and_b32_e32 v155, 0xffff0000, v183
	v_fmac_f32_e32 v147, v203, v143
	v_fma_f32 v148, v148, 0.5, -v152
	v_add_f32_e32 v149, v151, v149
	v_lshlrev_b32_e32 v158, 16, v187
	v_and_b32_e32 v157, 0xffff0000, v191
	v_cvt_pk_bf16_f32 v217, v146, v147
	v_fmac_f32_e32 v152, v204, v148
	v_fma_f32 v149, v149, 0.5, -v153
	v_add_f32_e32 v154, v156, v154
	v_and_b32_e32 v159, 0xffff0000, v187
	v_fmac_f32_e32 v153, v205, v149
	v_fma_f32 v154, v154, 0.5, -v158
	v_add_f32_e32 v155, v157, v155
	v_cvt_pk_bf16_f32 v218, v152, v153
	v_fmac_f32_e32 v158, v206, v154
	v_fma_f32 v155, v155, 0.5, -v159
	v_fmac_f32_e32 v159, v207, v155
	v_cvt_pk_bf16_f32 v219, v158, v159
	ds_write_b128 v223, v[216:219] offset:24576
	v_and_b32_e32 v160, 15, v1
	v_and_b32_e32 v161, -16, v1
	v_or_b32_e32 v162, s0, v160
	v_lshrrev_b32_e32 v163, 2, v1
	v_lshl_add_u32 v161, v162, 7, v161
	ds_read_b128 v[136:139], v161 offset:16384
	ds_read_b128 v[140:143], v161 offset:16448
	ds_read_b128 v[34:37], v224 offset:0
	ds_read_b128 v[38:41], v224 offset:1024
	ds_read_b128 v[42:45], v224 offset:2048
	ds_read_b128 v[46:49], v224 offset:3072
	ds_read_b128 v[50:53], v224 offset:4096
	ds_read_b128 v[54:57], v224 offset:5120
	ds_read_b128 v[58:61], v224 offset:6144
	ds_read_b128 v[62:65], v224 offset:7168
	v_lshlrev_b32_e32 v162, 2, v160
	v_and_b32_e32 v163, 0x1fffffc, v163
	v_add_u32_e32 v162, 0x22400, v162
	v_add_lshl_u32 v163, v163, s0, 7
	ds_read2_b32 v[152:153], v162 offset0:64 offset1:80
	ds_read2_b32 v[154:155], v162 offset0:96 offset1:112
	ds_read2_b32 v[156:157], v162 offset0:128 offset1:144
	ds_read2_b32 v[158:159], v162 offset0:160 offset1:176
	v_lshl_add_u32 v163, v160, 1, v163
	s_waitcnt lgkmcnt(10)
	v_mfma_f32_16x16x32_bf16 v[168:171], v[136:139], v[34:37], 0
	v_mfma_f32_16x16x32_bf16 v[168:171], v[140:143], v[38:41], v[168:171]
	s_waitcnt lgkmcnt(8)
	v_mfma_f32_16x16x32_bf16 v[172:175], v[136:139], v[42:45], 0
	v_mfma_f32_16x16x32_bf16 v[172:175], v[140:143], v[46:49], v[172:175]
	s_waitcnt lgkmcnt(0)
	ds_read_b128 v[144:147], v161 offset:24576
	ds_read_b128 v[148:151], v161 offset:24640
	ds_read_b128 v[66:69], v224 offset:8192
	ds_read_b128 v[70:73], v224 offset:9216
	ds_read_b128 v[74:77], v224 offset:10240
	ds_read_b128 v[78:81], v224 offset:11264
	ds_read_b128 v[82:85], v224 offset:12288
	ds_read_b128 v[86:89], v224 offset:13312
	ds_read_b128 v[90:93], v224 offset:14336
	ds_read_b128 v[94:97], v224 offset:15360
	s_nop 7
	v_add_f32_e32 v168, v168, v152
	v_mul_f32_e32 v168, 0xbfb8aa3b, v168
	v_add_f32_e32 v169, v169, v152
	v_exp_f32_e32 v168, v168
	v_mul_f32_e32 v169, 0xbfb8aa3b, v169
	v_add_f32_e32 v170, v170, v152
	v_add_f32_e32 v168, 1.0, v168
	v_exp_f32_e32 v169, v169
	v_mul_f32_e32 v170, 0xbfb8aa3b, v170
	v_add_f32_e32 v171, v171, v152
	v_rcp_f32_e32 v168, v168
	v_add_f32_e32 v169, 1.0, v169
	v_exp_f32_e32 v170, v170
	v_mul_f32_e32 v171, 0xbfb8aa3b, v171
	v_fma_mixlo_f16 v168, v168, s47, 0
	v_rcp_f32_e32 v169, v169
	v_add_f32_e32 v170, 1.0, v170
	v_exp_f32_e32 v171, v171
	ds_write_b16 v163, v168 offset:16384
	v_fma_mixlo_f16 v169, v169, s47, 0
	v_rcp_f32_e32 v170, v170
	v_add_f32_e32 v171, 1.0, v171
	ds_write_b16 v163, v169 offset:16512
	v_fma_mixlo_f16 v170, v170, s47, 0
	v_rcp_f32_e32 v171, v171
	ds_write_b16 v163, v170 offset:16640
	v_fma_mixlo_f16 v171, v171, s47, 0
	ds_write_b16 v163, v171 offset:16768
	v_mfma_f32_16x16x32_bf16 v[176:179], v[136:139], v[50:53], 0
	v_mfma_f32_16x16x32_bf16 v[176:179], v[140:143], v[54:57], v[176:179]
	v_add_f32_e32 v172, v172, v153
	v_mul_f32_e32 v172, 0xbfb8aa3b, v172
	v_add_f32_e32 v173, v173, v153
	v_exp_f32_e32 v172, v172
	v_mul_f32_e32 v173, 0xbfb8aa3b, v173
	v_add_f32_e32 v174, v174, v153
	v_add_f32_e32 v172, 1.0, v172
	v_exp_f32_e32 v173, v173
	v_mul_f32_e32 v174, 0xbfb8aa3b, v174
	v_add_f32_e32 v175, v175, v153
	v_rcp_f32_e32 v172, v172
	v_add_f32_e32 v173, 1.0, v173
	v_exp_f32_e32 v174, v174
	v_mul_f32_e32 v175, 0xbfb8aa3b, v175
	v_fma_mixlo_f16 v172, v172, s47, 0
	v_rcp_f32_e32 v173, v173
	v_add_f32_e32 v174, 1.0, v174
	v_exp_f32_e32 v175, v175
	ds_write_b16 v163, v172 offset:16416
	v_fma_mixlo_f16 v173, v173, s47, 0
	v_rcp_f32_e32 v174, v174
	v_add_f32_e32 v175, 1.0, v175
	ds_write_b16 v163, v173 offset:16544
	v_fma_mixlo_f16 v174, v174, s47, 0
	v_rcp_f32_e32 v175, v175
	ds_write_b16 v163, v174 offset:16672
	v_fma_mixlo_f16 v175, v175, s47, 0
	ds_write_b16 v163, v175 offset:16800
	v_mfma_f32_16x16x32_bf16 v[180:183], v[136:139], v[58:61], 0
	v_mfma_f32_16x16x32_bf16 v[180:183], v[140:143], v[62:65], v[180:183]
	v_add_f32_e32 v176, v176, v154
	v_mul_f32_e32 v176, 0xbfb8aa3b, v176
	v_add_f32_e32 v177, v177, v154
	v_exp_f32_e32 v176, v176
	v_mul_f32_e32 v177, 0xbfb8aa3b, v177
	v_add_f32_e32 v178, v178, v154
	v_add_f32_e32 v176, 1.0, v176
	v_exp_f32_e32 v177, v177
	v_mul_f32_e32 v178, 0xbfb8aa3b, v178
	v_add_f32_e32 v179, v179, v154
	v_rcp_f32_e32 v176, v176
	v_add_f32_e32 v177, 1.0, v177
	v_exp_f32_e32 v178, v178
	v_mul_f32_e32 v179, 0xbfb8aa3b, v179
	v_fma_mixlo_f16 v176, v176, s47, 0
	v_rcp_f32_e32 v177, v177
	v_add_f32_e32 v178, 1.0, v178
	v_exp_f32_e32 v179, v179
	ds_write_b16 v163, v176 offset:16448
	v_fma_mixlo_f16 v177, v177, s47, 0
	v_rcp_f32_e32 v178, v178
	v_add_f32_e32 v179, 1.0, v179
	ds_write_b16 v163, v177 offset:16576
	v_fma_mixlo_f16 v178, v178, s47, 0
	v_rcp_f32_e32 v179, v179
	ds_write_b16 v163, v178 offset:16704
	v_fma_mixlo_f16 v179, v179, s47, 0
	ds_write_b16 v163, v179 offset:16832
	s_waitcnt lgkmcnt(6)
	v_mfma_f32_16x16x32_bf16 v[184:187], v[144:147], v[66:69], 0
	v_mfma_f32_16x16x32_bf16 v[184:187], v[148:151], v[70:73], v[184:187]
	v_add_f32_e32 v180, v180, v155
	v_mul_f32_e32 v180, 0xbfb8aa3b, v180
	v_add_f32_e32 v181, v181, v155
	v_exp_f32_e32 v180, v180
	v_mul_f32_e32 v181, 0xbfb8aa3b, v181
	v_add_f32_e32 v182, v182, v155
	v_add_f32_e32 v180, 1.0, v180
	v_exp_f32_e32 v181, v181
	v_mul_f32_e32 v182, 0xbfb8aa3b, v182
	v_add_f32_e32 v183, v183, v155
	v_rcp_f32_e32 v180, v180
	v_add_f32_e32 v181, 1.0, v181
	v_exp_f32_e32 v182, v182
	v_mul_f32_e32 v183, 0xbfb8aa3b, v183
	v_fma_mixlo_f16 v180, v180, s47, 0
	v_rcp_f32_e32 v181, v181
	v_add_f32_e32 v182, 1.0, v182
	v_exp_f32_e32 v183, v183
	ds_write_b16 v163, v180 offset:16480
	v_fma_mixlo_f16 v181, v181, s47, 0
	v_rcp_f32_e32 v182, v182
	v_add_f32_e32 v183, 1.0, v183
	ds_write_b16 v163, v181 offset:16608
	v_fma_mixlo_f16 v182, v182, s47, 0
	v_rcp_f32_e32 v183, v183
	ds_write_b16 v163, v182 offset:16736
	v_fma_mixlo_f16 v183, v183, s47, 0
	ds_write_b16 v163, v183 offset:16864
	s_waitcnt lgkmcnt(4)
	v_mfma_f32_16x16x32_bf16 v[188:191], v[144:147], v[74:77], 0
	v_mfma_f32_16x16x32_bf16 v[188:191], v[148:151], v[78:81], v[188:191]
	v_add_f32_e32 v184, v184, v156
	v_mul_f32_e32 v184, 0xbfb8aa3b, v184
	v_add_f32_e32 v185, v185, v156
	v_exp_f32_e32 v184, v184
	v_mul_f32_e32 v185, 0xbfb8aa3b, v185
	v_add_f32_e32 v186, v186, v156
	v_add_f32_e32 v184, 1.0, v184
	v_exp_f32_e32 v185, v185
	v_mul_f32_e32 v186, 0xbfb8aa3b, v186
	v_add_f32_e32 v187, v187, v156
	v_rcp_f32_e32 v184, v184
	v_add_f32_e32 v185, 1.0, v185
	v_exp_f32_e32 v186, v186
	v_mul_f32_e32 v187, 0xbfb8aa3b, v187
	v_rcp_f32_e32 v185, v185
	v_add_f32_e32 v186, 1.0, v186
	v_exp_f32_e32 v187, v187
	v_cvt_pk_f16_f32 v184, v184, v185
	v_rcp_f32_e32 v186, v186
	v_add_f32_e32 v187, 1.0, v187
	ds_write_b16 v163, v184 offset:24576
	v_rcp_f32_e32 v187, v187
	ds_write_b16_d16_hi v163, v184 offset:24704
	v_cvt_pk_f16_f32 v186, v186, v187
	ds_write_b16 v163, v186 offset:24832
	ds_write_b16_d16_hi v163, v186 offset:24960
	s_waitcnt lgkmcnt(2)
	v_mfma_f32_16x16x32_bf16 v[192:195], v[144:147], v[82:85], 0
	v_mfma_f32_16x16x32_bf16 v[192:195], v[148:151], v[86:89], v[192:195]
	v_add_f32_e32 v188, v188, v157
	v_mul_f32_e32 v188, 0xbfb8aa3b, v188
	v_add_f32_e32 v189, v189, v157
	v_exp_f32_e32 v188, v188
	v_mul_f32_e32 v189, 0xbfb8aa3b, v189
	v_add_f32_e32 v190, v190, v157
	v_add_f32_e32 v188, 1.0, v188
	v_exp_f32_e32 v189, v189
	v_mul_f32_e32 v190, 0xbfb8aa3b, v190
	v_add_f32_e32 v191, v191, v157
	v_rcp_f32_e32 v188, v188
	v_add_f32_e32 v189, 1.0, v189
	v_exp_f32_e32 v190, v190
	v_mul_f32_e32 v191, 0xbfb8aa3b, v191
	v_rcp_f32_e32 v189, v189
	v_add_f32_e32 v190, 1.0, v190
	v_exp_f32_e32 v191, v191
	v_cvt_pk_f16_f32 v188, v188, v189
	v_rcp_f32_e32 v190, v190
	v_add_f32_e32 v191, 1.0, v191
	ds_write_b16 v163, v188 offset:24608
	v_rcp_f32_e32 v191, v191
	ds_write_b16_d16_hi v163, v188 offset:24736
	v_cvt_pk_f16_f32 v190, v190, v191
	ds_write_b16 v163, v190 offset:24864
	ds_write_b16_d16_hi v163, v190 offset:24992
	s_waitcnt lgkmcnt(0)
	v_mfma_f32_16x16x32_bf16 v[196:199], v[144:147], v[90:93], 0
	v_mfma_f32_16x16x32_bf16 v[196:199], v[148:151], v[94:97], v[196:199]
	v_add_f32_e32 v192, v192, v158
	v_mul_f32_e32 v192, 0xbfb8aa3b, v192
	v_add_f32_e32 v193, v193, v158
	v_exp_f32_e32 v192, v192
	v_mul_f32_e32 v193, 0xbfb8aa3b, v193
	v_add_f32_e32 v194, v194, v158
	v_add_f32_e32 v192, 1.0, v192
	v_exp_f32_e32 v193, v193
	v_mul_f32_e32 v194, 0xbfb8aa3b, v194
	v_add_f32_e32 v195, v195, v158
	v_rcp_f32_e32 v192, v192
	v_add_f32_e32 v193, 1.0, v193
	v_exp_f32_e32 v194, v194
	v_mul_f32_e32 v195, 0xbfb8aa3b, v195
	v_rcp_f32_e32 v193, v193
	v_add_f32_e32 v194, 1.0, v194
	v_exp_f32_e32 v195, v195
	v_cvt_pk_f16_f32 v192, v192, v193
	v_rcp_f32_e32 v194, v194
	v_add_f32_e32 v195, 1.0, v195
	ds_write_b16 v163, v192 offset:24640
	v_rcp_f32_e32 v195, v195
	ds_write_b16_d16_hi v163, v192 offset:24768
	v_cvt_pk_f16_f32 v194, v194, v195
	ds_write_b16 v163, v194 offset:24896
	ds_write_b16_d16_hi v163, v194 offset:25024
	v_add_f32_e32 v196, v196, v159
	v_mul_f32_e32 v196, 0xbfb8aa3b, v196
	v_add_f32_e32 v197, v197, v159
	v_exp_f32_e32 v196, v196
	v_mul_f32_e32 v197, 0xbfb8aa3b, v197
	v_add_f32_e32 v198, v198, v159
	v_add_f32_e32 v196, 1.0, v196
	v_exp_f32_e32 v197, v197
	v_mul_f32_e32 v198, 0xbfb8aa3b, v198
	v_add_f32_e32 v199, v199, v159
	v_rcp_f32_e32 v196, v196
	v_add_f32_e32 v197, 1.0, v197
	v_exp_f32_e32 v198, v198
	v_mul_f32_e32 v199, 0xbfb8aa3b, v199
	v_rcp_f32_e32 v197, v197
	v_add_f32_e32 v198, 1.0, v198
	v_exp_f32_e32 v199, v199
	v_cvt_pk_f16_f32 v196, v196, v197
	v_rcp_f32_e32 v198, v198
	v_add_f32_e32 v199, 1.0, v199
	ds_write_b16 v163, v196 offset:24672
	v_rcp_f32_e32 v199, v199
	ds_write_b16_d16_hi v163, v196 offset:24800
	v_cvt_pk_f16_f32 v198, v198, v199
	ds_write_b16 v163, v198 offset:24928
	ds_write_b16_d16_hi v163, v198 offset:25056
